# NSA compressed-branch pass 1: the 32 bias-table LDS lookups per tile issued up front (were 32 dependent read-wait-fma round trips)
# speedup vs baseline: 1.0011x; 1.0011x over previous
; #define LAS __attribute__((address_space(3)))
; __device__ __forceinline__ int crow(int r, int hi) { return (r & 3) + 8 * (r >> 2) + 4 * hi; }
; __device__ __forceinline__ v16f mfma32(v8s a, v8s b, v16f c) { return __builtin_amdgcn_mfma_f32_32x32x16_bf16(a, b, c, 0, 0, 0); }
; __device__ __forceinline__ void qk_tile(const LAS unsigned char* Kt, const v8s (&qf)[4], v16f& p0, v16f& p1, int r32, int hi) {
;     ...
;     for (int s = 0; s < 4; ++s) {
;         const v8s a0 = *(const LAS v8s*)(kb + s * 32);
;         const v8s a1 = *(const LAS v8s*)(kb + 32 * KP + s * 32);
;         p0 = mfma32(a0, qf[s], p0); p1 = mfma32(a1, qf[s], p1);
;     }
; __device__ __forceinline__ void nsa_phase(LAS unsigned char* lds, const bf16_t* QKV, const float* relb, const bf16_t* KCMP, const bf16_t* VCMP, bf16_t* AO, float* SCRG, unsigned* CTR, const float* sinks) {
;     ...
;                 qk_tile(KT + buf * KTB, qf, p0, p1, r32, hi);
;                 float mx = -INFINITY;
; #pragma unroll
;                 for (int r = 0; r < 16; ++r) {
;                     const int c0 = 64 * t + crow(r, hi); const int d0 = qpos - 16 * c0 - 31, d1 = d0 - 512;
;                     p0[r] = p0[r] * C1 + tb[min(max(d0, -1), 1024)]; p1[r] = p1[r] * C1 + tb[min(max(d1, -1), 1024)];
;                     mx = fmaxf(mx, fmaxf(p0[r], p1[r]));
.LBB0_495:
	v_add3_u32 v41, s21, v43, v44
	ds_read_b128 v[2:5], v41 offset:4608
	ds_read_b128 v[6:9], v41
	ds_read_b128 v[48:51], v41 offset:32
	ds_read_b128 v[52:55], v41 offset:4640
	s_add_i32 s19, s19, 1
	v_add_u32_e32 v40, 64, v40
	s_waitcnt lgkmcnt(2)
	v_mfma_f32_32x32x16_bf16 v[18:33], v[6:9], v[130:133], 0
	s_cmp_eq_u32 s20, s19
	v_mfma_f32_32x32x16_bf16 v[2:17], v[2:5], v[130:133], 0
	s_waitcnt lgkmcnt(1)
	v_mfma_f32_32x32x16_bf16 v[18:33], v[48:51], v[134:137], v[18:33]
	s_waitcnt lgkmcnt(0)
	v_mfma_f32_32x32x16_bf16 v[2:17], v[52:55], v[134:137], v[2:17]
	ds_read_b128 v[48:51], v41 offset:64
	ds_read_b128 v[52:55], v41 offset:4672
	s_waitcnt lgkmcnt(1)
	v_mfma_f32_32x32x16_bf16 v[18:33], v[48:51], v[138:141], v[18:33]
	s_waitcnt lgkmcnt(0)
	v_mfma_f32_32x32x16_bf16 v[2:17], v[52:55], v[138:141], v[2:17]
	ds_read_b128 v[48:51], v41 offset:96
	ds_read_b128 v[52:55], v41 offset:4704
	s_waitcnt lgkmcnt(1)
	v_mfma_f32_32x32x16_bf16 v[18:33], v[48:51], v[142:145], v[18:33]
	v_add_u32_e32 v178, 0x1b0, v45
	v_med3_i32 v178, v178, 30, v242
	v_lshl_add_u32 v178, v178, 2, s37
	ds_read_b32 v146, v178 offset:53636
	v_add_u32_e32 v179, 0x1b0, v45
	v_med3_i32 v179, v179, s33, v243
	v_lshl_add_u32 v179, v179, 2, s37
	ds_read_b32 v147, v179 offset:51588
	v_add_u32_e32 v180, 0x1a0, v45
	v_med3_i32 v180, v180, 30, v242
	v_lshl_add_u32 v180, v180, 2, s37
	ds_read_b32 v148, v180 offset:53636
	v_add_u32_e32 v181, 0x1a0, v45
	v_med3_i32 v181, v181, s33, v243
	v_lshl_add_u32 v181, v181, 2, s37
	ds_read_b32 v149, v181 offset:51588
	v_add_u32_e32 v178, 0x190, v45
	v_med3_i32 v178, v178, 30, v242
	v_lshl_add_u32 v178, v178, 2, s37
	ds_read_b32 v150, v178 offset:53636
	v_add_u32_e32 v179, 0x190, v45
	v_med3_i32 v179, v179, s33, v243
	v_lshl_add_u32 v179, v179, 2, s37
	ds_read_b32 v151, v179 offset:51588
	v_add_u32_e32 v180, 0x180, v45
	v_med3_i32 v180, v180, 30, v242
	v_lshl_add_u32 v180, v180, 2, s37
	ds_read_b32 v152, v180 offset:53636
	v_add_u32_e32 v181, 0x180, v45
	v_med3_i32 v181, v181, s33, v243
	v_lshl_add_u32 v181, v181, 2, s37
	ds_read_b32 v153, v181 offset:51588
	v_add_u32_e32 v178, 0x130, v45
	v_med3_i32 v178, v178, 30, v242
	v_lshl_add_u32 v178, v178, 2, s37
	ds_read_b32 v154, v178 offset:53636
	v_add_u32_e32 v179, 0x130, v45
	v_med3_i32 v179, v179, s33, v243
	v_lshl_add_u32 v179, v179, 2, s37
	ds_read_b32 v155, v179 offset:51588
	v_add_u32_e32 v180, 0x120, v45
	v_med3_i32 v180, v180, 30, v242
	v_lshl_add_u32 v180, v180, 2, s37
	ds_read_b32 v156, v180 offset:53636
	v_add_u32_e32 v181, 0x120, v45
	v_med3_i32 v181, v181, s33, v243
	v_lshl_add_u32 v181, v181, 2, s37
	ds_read_b32 v157, v181 offset:51588
	v_add_u32_e32 v178, 0x110, v45
	v_med3_i32 v178, v178, 30, v242
	v_lshl_add_u32 v178, v178, 2, s37
	ds_read_b32 v158, v178 offset:53636
	v_add_u32_e32 v179, 0x110, v45
	v_med3_i32 v179, v179, s33, v243
	v_lshl_add_u32 v179, v179, 2, s37
	ds_read_b32 v159, v179 offset:51588
	v_add_u32_e32 v180, 0x100, v45
	v_med3_i32 v180, v180, 30, v242
	v_lshl_add_u32 v180, v180, 2, s37
	ds_read_b32 v160, v180 offset:53636
	v_add_u32_e32 v181, 0x100, v45
	v_med3_i32 v181, v181, s33, v243
	v_lshl_add_u32 v181, v181, 2, s37
	ds_read_b32 v161, v181 offset:51588
	v_add_u32_e32 v178, 0xb0, v45
	v_med3_i32 v178, v178, 30, v242
	v_lshl_add_u32 v178, v178, 2, s37
	ds_read_b32 v162, v178 offset:53636
	v_add_u32_e32 v179, 0xa0, v45
	v_med3_i32 v179, v179, 30, v242
	v_lshl_add_u32 v179, v179, 2, s37
	ds_read_b32 v163, v179 offset:53636
	v_add_u32_e32 v180, 0xb0, v45
	v_med3_i32 v180, v180, s33, v243
	v_lshl_add_u32 v180, v180, 2, s37
	ds_read_b32 v164, v180 offset:51588
	v_add_u32_e32 v181, 0xa0, v45
	v_med3_i32 v181, v181, s33, v243
	v_lshl_add_u32 v181, v181, 2, s37
	ds_read_b32 v165, v181 offset:51588
	v_add_u32_e32 v178, 0x90, v45
	v_med3_i32 v178, v178, 30, v242
	v_lshl_add_u32 v178, v178, 2, s37
	ds_read_b32 v166, v178 offset:53636
	v_add_u32_e32 v179, 0x90, v45
	v_med3_i32 v179, v179, s33, v243
	v_lshl_add_u32 v179, v179, 2, s37
	ds_read_b32 v167, v179 offset:51588
	v_add_u32_e32 v180, 0x80, v45
	v_med3_i32 v180, v180, 30, v242
	v_lshl_add_u32 v180, v180, 2, s37
	ds_read_b32 v168, v180 offset:53636
	v_add_u32_e32 v181, 0x80, v45
	v_med3_i32 v181, v181, s33, v243
	v_lshl_add_u32 v181, v181, 2, s37
	ds_read_b32 v169, v181 offset:51588
	v_add_u32_e32 v178, 48, v45
	v_med3_i32 v178, v178, 30, v242
	v_lshl_add_u32 v178, v178, 2, s37
	ds_read_b32 v170, v178 offset:53636
	v_add_u32_e32 v179, 48, v45
	v_med3_i32 v179, v179, s33, v243
	v_lshl_add_u32 v179, v179, 2, s37
	ds_read_b32 v171, v179 offset:51588
	v_add_u32_e32 v180, 32, v45
	v_med3_i32 v180, v180, 30, v242
	v_lshl_add_u32 v180, v180, 2, s37
	ds_read_b32 v172, v180 offset:53636
	v_add_u32_e32 v181, 32, v45
	v_med3_i32 v181, v181, s33, v243
	v_lshl_add_u32 v181, v181, 2, s37
	ds_read_b32 v173, v181 offset:51588
	v_add_u32_e32 v178, 16, v45
	v_med3_i32 v178, v178, 30, v242
	v_lshl_add_u32 v178, v178, 2, s37
	ds_read_b32 v174, v178 offset:53636
	v_add_u32_e32 v179, 0, v45
	v_med3_i32 v179, v179, 30, v242
	v_lshl_add_u32 v179, v179, 2, s37
	ds_read_b32 v175, v179 offset:53636
	v_add_u32_e32 v180, 16, v45
	v_med3_i32 v180, v180, s33, v243
	v_lshl_add_u32 v180, v180, 2, s37
	ds_read_b32 v176, v180 offset:51588
	v_add_u32_e32 v181, 0, v45
	v_med3_i32 v181, v181, s33, v243
	v_lshl_add_u32 v181, v181, 2, s37
	ds_read_b32 v177, v181 offset:51588
	v_add_u32_e32 v48, 0x1b0, v45
	v_med3_i32 v41, v48, 30, v242
	v_lshl_add_u32 v41, v41, 2, s37
	v_add_u32_e32 v49, 0x1a0, v45
	v_add_u32_e32 v50, 0x180, v45
	s_waitcnt lgkmcnt(0)
	s_nop 4
	v_fma_f32 v41, v18, s52, v146
	v_mfma_f32_32x32x16_bf16 v[2:17], v[52:55], v[142:145], v[2:17]
	s_waitcnt lgkmcnt(0)
; __device__ __forceinline__ float ex2(float x) { return __builtin_amdgcn_exp2f(x); }
; __device__ __forceinline__ int crow(int r, int hi) { return (r & 3) + 8 * (r >> 2) + 4 * hi; }
; __device__ __forceinline__ void nsa_phase(LAS unsigned char* lds, const bf16_t* QKV, const float* relb, const bf16_t* KCMP, const bf16_t* VCMP, bf16_t* AO, float* SCRG, unsigned* CTR, const float* sinks) {
;     ...
;                 for (int r = 0; r < 16; ++r) {
;                     const int c0 = 64 * t + crow(r, hi); const int d0 = qpos - 16 * c0 - 31, d1 = d0 - 512;
;                     p0[r] = p0[r] * C1 + tb[min(max(d0, -1), 1024)]; p1[r] = p1[r] * C1 + tb[min(max(d1, -1), 1024)];
;                     mx = fmaxf(mx, fmaxf(p0[r], p1[r]));
;                 }
;                 mx = xhalf_max(mx);
;                 const float mn = fmaxf(m, mx), mu = (mn == -INFINITY) ? 0.f : mn;
;                 float rs = 0.f;
; #pragma unroll
;                 for (int r = 0; r < 16; ++r) rs += ex2(p0[r] - mu) + ex2(p1[r] - mu);
;                 l = l * ex2(m - mu) + rs; m = mn;
	s_nop 7
	v_med3_i32 v18, v48, s33, v243
	v_lshl_add_u32 v18, v18, 2, s37
	s_nop 7
	v_fma_f32 v18, v2, s52, v147
	v_med3_i32 v2, v49, 30, v242
	v_lshl_add_u32 v2, v2, 2, s37
	v_max_f32_e32 v48, v41, v18
	v_fma_f32 v2, v19, s52, v148
	v_med3_i32 v19, v49, s33, v243
	v_lshl_add_u32 v19, v19, 2, s37
	v_add_u32_e32 v49, 0x190, v45
	v_fma_f32 v19, v3, s52, v149
	v_max_f32_e32 v3, v2, v19
	v_max3_f32 v48, v48, s76, v3
	v_med3_i32 v3, v49, 30, v242
	v_lshl_add_u32 v3, v3, 2, s37
	v_fma_f32 v3, v20, s52, v150
	v_med3_i32 v20, v49, s33, v243
	v_lshl_add_u32 v20, v20, 2, s37
	v_fma_f32 v20, v4, s52, v151
	v_med3_i32 v4, v50, 30, v242
	v_lshl_add_u32 v4, v4, 2, s37
	v_max_f32_e32 v49, v3, v20
	v_fma_f32 v4, v21, s52, v152
	v_med3_i32 v21, v50, s33, v243
	v_lshl_add_u32 v21, v21, 2, s37
	v_add_u32_e32 v50, 0x120, v45
	v_fma_f32 v21, v5, s52, v153
	v_max_f32_e32 v5, v4, v21
	v_max3_f32 v48, v48, v49, v5
	v_add_u32_e32 v49, 0x130, v45
	v_med3_i32 v5, v49, 30, v242
	v_lshl_add_u32 v5, v5, 2, s37
	v_fma_f32 v5, v22, s52, v154
	v_med3_i32 v22, v49, s33, v243
	v_lshl_add_u32 v22, v22, 2, s37
	v_fma_f32 v22, v6, s52, v155
	v_med3_i32 v6, v50, 30, v242
	v_lshl_add_u32 v6, v6, 2, s37
	v_max_f32_e32 v49, v5, v22
	v_fma_f32 v6, v23, s52, v156
	v_med3_i32 v23, v50, s33, v243
	v_lshl_add_u32 v23, v23, 2, s37
	v_add_u32_e32 v50, 0x100, v45
	v_fma_f32 v23, v7, s52, v157
	v_max_f32_e32 v7, v6, v23
	v_max3_f32 v48, v48, v49, v7
	v_add_u32_e32 v49, 0x110, v45
	v_med3_i32 v7, v49, 30, v242
	v_lshl_add_u32 v7, v7, 2, s37
	v_fma_f32 v7, v24, s52, v158
	v_med3_i32 v24, v49, s33, v243
	v_lshl_add_u32 v24, v24, 2, s37
	v_fma_f32 v24, v8, s52, v159
	v_med3_i32 v8, v50, 30, v242
	v_lshl_add_u32 v8, v8, 2, s37
	v_max_f32_e32 v49, v7, v24
	v_fma_f32 v8, v25, s52, v160
	v_med3_i32 v25, v50, s33, v243
	v_lshl_add_u32 v25, v25, 2, s37
	v_fma_f32 v25, v9, s52, v161
	v_max_f32_e32 v9, v8, v25
	v_max3_f32 v9, v48, v49, v9
	v_add_u32_e32 v48, 0xb0, v45
	v_med3_i32 v49, v48, 30, v242
	v_lshl_add_u32 v49, v49, 2, s37
	v_fma_f32 v49, v26, s52, v162
	v_med3_i32 v26, v48, s33, v243
	v_add_u32_e32 v48, 0xa0, v45
	v_med3_i32 v50, v48, 30, v242
	v_lshl_add_u32 v50, v50, 2, s37
	v_lshl_add_u32 v26, v26, 2, s37
	v_fma_f32 v50, v27, s52, v163
	v_med3_i32 v27, v48, s33, v243
	v_lshl_add_u32 v27, v27, 2, s37
	v_fma_f32 v26, v10, s52, v164
	v_max_f32_e32 v10, v49, v26
	v_fma_f32 v27, v11, s52, v165
	v_max_f32_e32 v11, v50, v27
	v_max3_f32 v9, v9, v10, v11
	v_add_u32_e32 v10, 0x90, v45
	v_med3_i32 v11, v10, 30, v242
	v_lshl_add_u32 v11, v11, 2, s37
	v_med3_i32 v10, v10, s33, v243
	v_lshl_add_u32 v10, v10, 2, s37
	v_fma_f32 v11, v28, s52, v166
	v_add_u32_e32 v28, 0x80, v45
	v_med3_i32 v48, v28, 30, v242
	v_med3_i32 v28, v28, s33, v243
	v_lshl_add_u32 v48, v48, 2, s37
	v_lshl_add_u32 v28, v28, 2, s37
	v_fma_f32 v10, v12, s52, v167
	v_max_f32_e32 v12, v11, v10
	v_fma_f32 v48, v29, s52, v168
	v_fma_f32 v28, v13, s52, v169
	v_max_f32_e32 v13, v48, v28
	v_max3_f32 v9, v9, v12, v13
	v_add_u32_e32 v12, 48, v45
	v_med3_i32 v13, v12, 30, v242
	v_lshl_add_u32 v13, v13, 2, s37
	v_med3_i32 v12, v12, s33, v243
	v_lshl_add_u32 v12, v12, 2, s37
	v_add_u32_e32 v29, 32, v45
	v_fma_f32 v13, v30, s52, v170
	v_med3_i32 v30, v29, 30, v242
	v_med3_i32 v29, v29, s33, v243
	v_lshl_add_u32 v30, v30, 2, s37
	v_lshl_add_u32 v29, v29, 2, s37
	v_fma_f32 v12, v14, s52, v171
	v_max_f32_e32 v14, v13, v12
	v_fma_f32 v30, v31, s52, v172
	v_fma_f32 v29, v15, s52, v173
	v_max_f32_e32 v15, v30, v29
	v_max3_f32 v9, v9, v14, v15
	v_add_u32_e32 v14, 16, v45
	v_med3_i32 v15, v14, 30, v242
	v_lshl_add_u32 v15, v15, 2, s37
	v_med3_i32 v14, v14, s33, v243
	v_med3_i32 v31, v45, 30, v242
	v_lshl_add_u32 v14, v14, 2, s37
	v_lshl_add_u32 v31, v31, 2, s37
	v_fma_f32 v15, v32, s52, v174
	v_med3_i32 v32, v45, s33, v243
	v_lshl_add_u32 v32, v32, 2, s37
	v_fma_f32 v14, v16, s52, v176
	v_fma_f32 v31, v33, s52, v175
	v_max_f32_e32 v16, v15, v14
	v_add_u32_e32 v45, 0xfffffc00, v45
	v_fma_f32 v32, v17, s52, v177
	v_max_f32_e32 v17, v31, v32
	v_max3_f32 v9, v9, v16, v17
	v_mov_b32_e32 v16, v9
	s_nop 1
	v_permlane32_swap_b32_e32 v9, v16
	v_max3_f32 v9, v47, v9, v16
	v_cmp_neq_f32_e32 vcc, s76, v9
	s_nop 1
	v_cndmask_b32_e32 v75, 0, v9, vcc
	v_sub_f32_e32 v16, v41, v75
	v_sub_f32_e32 v17, v18, v75
	v_exp_f32_e32 v16, v16
	v_exp_f32_e32 v17, v17
	v_sub_f32_e32 v2, v2, v75
	v_exp_f32_e32 v2, v2
	v_sub_f32_e32 v3, v3, v75
	v_add_f32_e32 v16, v16, v17
	v_sub_f32_e32 v17, v19, v75
	v_exp_f32_e32 v17, v17
	v_add_f32_e32 v16, 0, v16
	v_exp_f32_e32 v3, v3
	v_add_f32_e32 v2, v2, v17
	v_add_f32_e32 v2, v2, v16
	v_sub_f32_e32 v16, v20, v75
	v_exp_f32_e32 v16, v16
	s_nop 0
	v_add_f32_e32 v3, v3, v16
	v_add_f32_e32 v2, v3, v2
	v_sub_f32_e32 v3, v4, v75
	v_sub_f32_e32 v4, v21, v75
	v_exp_f32_e32 v3, v3
	v_exp_f32_e32 v4, v4
	s_nop 0
	v_add_f32_e32 v3, v3, v4
	v_add_f32_e32 v3, v3, v2
	v_sub_f32_e32 v2, v5, v75
	v_sub_f32_e32 v4, v22, v75
	v_exp_f32_e32 v2, v2
	v_exp_f32_e32 v4, v4
	s_nop 0
	v_add_f32_e32 v5, v2, v4
	v_sub_f32_e32 v2, v6, v75
	v_exp_f32_e32 v4, v2
	v_sub_f32_e32 v2, v23, v75
	v_exp_f32_e32 v2, v2
	s_nop 0
	v_pk_add_f32 v[2:3], v[4:5], v[2:3]
	s_nop 0
	v_pk_add_f32 v[2:3], v[2:3], v[2:3] op_sel_hi:[0,1]
	v_sub_f32_e32 v2, v7, v75
	v_sub_f32_e32 v4, v24, v75
	v_exp_f32_e32 v2, v2
	v_exp_f32_e32 v4, v4
	s_nop 0
	v_add_f32_e32 v5, v2, v4
	v_sub_f32_e32 v2, v8, v75
	v_exp_f32_e32 v4, v2
	v_sub_f32_e32 v2, v25, v75
	v_exp_f32_e32 v2, v2
	s_nop 0
	v_pk_add_f32 v[2:3], v[4:5], v[2:3]
	s_nop 0
	v_pk_add_f32 v[2:3], v[2:3], v[2:3] op_sel_hi:[0,1]
	v_sub_f32_e32 v2, v49, v75
	v_sub_f32_e32 v4, v26, v75
	v_exp_f32_e32 v2, v2
	v_exp_f32_e32 v4, v4
	s_nop 0
	v_add_f32_e32 v5, v2, v4
	v_sub_f32_e32 v2, v50, v75
	v_exp_f32_e32 v4, v2
	v_sub_f32_e32 v2, v27, v75
	v_exp_f32_e32 v2, v2
	s_nop 0
	v_pk_add_f32 v[2:3], v[4:5], v[2:3]
	s_nop 0
	v_pk_add_f32 v[2:3], v[2:3], v[2:3] op_sel_hi:[0,1]
	v_sub_f32_e32 v2, v11, v75
	v_sub_f32_e32 v4, v10, v75
	v_exp_f32_e32 v2, v2
	v_exp_f32_e32 v4, v4
	s_nop 0
	v_add_f32_e32 v5, v2, v4
	v_sub_f32_e32 v2, v48, v75
	v_exp_f32_e32 v4, v2
	v_sub_f32_e32 v2, v28, v75
	v_exp_f32_e32 v2, v2
	s_nop 0
	v_pk_add_f32 v[2:3], v[4:5], v[2:3]
	s_nop 0
	v_pk_add_f32 v[2:3], v[2:3], v[2:3] op_sel_hi:[0,1]
	v_sub_f32_e32 v2, v13, v75
	v_sub_f32_e32 v4, v12, v75
	v_exp_f32_e32 v2, v2
	v_exp_f32_e32 v4, v4
	s_nop 0
	v_add_f32_e32 v5, v2, v4
	v_sub_f32_e32 v2, v30, v75
	v_exp_f32_e32 v4, v2
	v_sub_f32_e32 v2, v29, v75
	v_exp_f32_e32 v2, v2
	s_nop 0
	v_pk_add_f32 v[2:3], v[4:5], v[2:3]
	s_nop 0
	v_pk_add_f32 v[2:3], v[2:3], v[2:3] op_sel_hi:[0,1]
	v_sub_f32_e32 v2, v15, v75
	v_sub_f32_e32 v4, v14, v75
	v_exp_f32_e32 v2, v2
	v_exp_f32_e32 v4, v4
	s_nop 0
	v_add_f32_e32 v5, v2, v4
	v_sub_f32_e32 v2, v31, v75
	v_exp_f32_e32 v4, v2
	v_sub_f32_e32 v2, v32, v75
	v_exp_f32_e32 v2, v2
	s_nop 0
	v_pk_add_f32 v[2:3], v[4:5], v[2:3]
	s_nop 0
	v_add_f32_e32 v3, v2, v3
	v_sub_f32_e32 v2, v47, v75
	v_exp_f32_e32 v2, v2
	s_nop 0
	v_fmac_f32_e32 v3, v46, v2
	s_cbranch_scc1 .LBB0_497
	v_mov_b32_e32 v47, v9
	v_mov_b32_e32 v46, v3
	s_branch .LBB0_493
